# P2b gelu pre-pass: 2/(e+1) via v_rcp_f32 (f32, same reciprocal the baseline sigmoid uses) instead of the div_scale/fmas/fixup sequence
# baseline (speedup 1.0000x reference)
.LBB0_712:
	v_and_b32_e32 v0, 0xf8, v157
	v_lshlrev_b32_e32 v128, 2, v0
	v_add_u32_e32 v0, s6, v164
	v_ashrrev_i32_e32 v1, 31, v0
	v_lshl_add_u64 v[20:21], s[82:83], 0, v[128:129]
	v_lshlrev_b64 v[2:3], 10, v[0:1]
	v_lshl_add_u64 v[2:3], v[20:21], 0, v[2:3]
	global_load_dwordx4 v[96:99], v[2:3], off offset:16
	global_load_dwordx4 v[104:107], v[2:3], off
	v_add_u32_e32 v2, 0x2000, v0
	v_ashrrev_i32_e32 v3, 31, v2
	v_lshlrev_b64 v[2:3], 10, v[2:3]
	v_lshl_add_u64 v[2:3], v[20:21], 0, v[2:3]
	global_load_dwordx4 v[100:103], v[2:3], off offset:16
	global_load_dwordx4 v[112:115], v[2:3], off
	v_add_u32_e32 v2, 0x4000, v0
	v_add_u32_e32 v0, 0x6000, v0
	v_ashrrev_i32_e32 v3, 31, v2
	v_ashrrev_i32_e32 v1, 31, v0
	v_lshlrev_b64 v[2:3], 10, v[2:3]
	v_lshlrev_b64 v[0:1], 10, v[0:1]
	v_lshl_add_u64 v[2:3], v[20:21], 0, v[2:3]
	v_lshl_add_u64 v[0:1], v[20:21], 0, v[0:1]
	global_load_dwordx4 v[108:111], v[2:3], off offset:16
	global_load_dwordx4 v[120:123], v[2:3], off
	global_load_dwordx4 v[116:119], v[0:1], off offset:16
	global_load_dwordx4 v[124:127], v[0:1], off
	v_add_u32_e32 v0, s6, v159
	v_ashrrev_i32_e32 v1, 31, v0
	v_lshlrev_b64 v[2:3], 10, v[0:1]
	v_lshl_add_u64 v[2:3], v[20:21], 0, v[2:3]
	global_load_dwordx4 v[64:67], v[2:3], off offset:16
	global_load_dwordx4 v[72:75], v[2:3], off
	v_add_u32_e32 v2, 0x2000, v0
	v_ashrrev_i32_e32 v3, 31, v2
	v_lshlrev_b64 v[2:3], 10, v[2:3]
	v_lshl_add_u64 v[2:3], v[20:21], 0, v[2:3]
	global_load_dwordx4 v[68:71], v[2:3], off offset:16
	global_load_dwordx4 v[80:83], v[2:3], off
	v_add_u32_e32 v2, 0x4000, v0
	v_add_u32_e32 v0, 0x6000, v0
	v_ashrrev_i32_e32 v3, 31, v2
	v_ashrrev_i32_e32 v1, 31, v0
	v_lshlrev_b64 v[2:3], 10, v[2:3]
	v_lshlrev_b64 v[0:1], 10, v[0:1]
	v_lshl_add_u64 v[2:3], v[20:21], 0, v[2:3]
	v_lshl_add_u64 v[0:1], v[20:21], 0, v[0:1]
	global_load_dwordx4 v[76:79], v[2:3], off offset:16
	global_load_dwordx4 v[88:91], v[2:3], off
	global_load_dwordx4 v[84:87], v[0:1], off offset:16
	global_load_dwordx4 v[92:95], v[0:1], off
	v_add_u32_e32 v0, s6, v162
	v_ashrrev_i32_e32 v1, 31, v0
	v_lshlrev_b64 v[2:3], 10, v[0:1]
	v_lshl_add_u64 v[2:3], v[20:21], 0, v[2:3]
	global_load_dwordx4 v[32:35], v[2:3], off offset:16
	global_load_dwordx4 v[40:43], v[2:3], off
	v_add_u32_e32 v2, 0x2000, v0
	v_ashrrev_i32_e32 v3, 31, v2
	v_lshlrev_b64 v[2:3], 10, v[2:3]
	v_lshl_add_u64 v[2:3], v[20:21], 0, v[2:3]
	global_load_dwordx4 v[36:39], v[2:3], off offset:16
	global_load_dwordx4 v[48:51], v[2:3], off
	v_add_u32_e32 v2, 0x4000, v0
	v_add_u32_e32 v0, 0x6000, v0
	v_ashrrev_i32_e32 v3, 31, v2
	v_ashrrev_i32_e32 v1, 31, v0
	v_lshlrev_b64 v[2:3], 10, v[2:3]
	v_lshlrev_b64 v[0:1], 10, v[0:1]
	v_add_u32_e32 v22, s6, v163
	v_lshl_add_u64 v[2:3], v[20:21], 0, v[2:3]
	v_lshl_add_u64 v[0:1], v[20:21], 0, v[0:1]
	v_ashrrev_i32_e32 v23, 31, v22
	global_load_dwordx4 v[44:47], v[2:3], off offset:16
	global_load_dwordx4 v[56:59], v[2:3], off
	global_load_dwordx4 v[52:55], v[0:1], off offset:16
	global_load_dwordx4 v[60:63], v[0:1], off
	v_lshlrev_b64 v[0:1], 10, v[22:23]
	v_lshl_add_u64 v[4:5], v[20:21], 0, v[0:1]
	global_load_dwordx4 v[0:3], v[4:5], off offset:16
	global_load_dwordx4 v[8:11], v[4:5], off
	v_add_u32_e32 v4, 0x2000, v22
	v_ashrrev_i32_e32 v5, 31, v4
	v_lshlrev_b64 v[4:5], 10, v[4:5]
	v_lshl_add_u64 v[12:13], v[20:21], 0, v[4:5]
	global_load_dwordx4 v[4:7], v[12:13], off offset:16
	global_load_dwordx4 v[16:19], v[12:13], off
	v_add_u32_e32 v12, 0x4000, v22
	v_add_u32_e32 v22, 0x6000, v22
	v_ashrrev_i32_e32 v13, 31, v12
	v_ashrrev_i32_e32 v23, 31, v22
	v_lshlrev_b64 v[12:13], 10, v[12:13]
	v_lshlrev_b64 v[22:23], 10, v[22:23]
	v_lshl_add_u64 v[24:25], v[20:21], 0, v[12:13]
	v_lshl_add_u64 v[28:29], v[20:21], 0, v[22:23]
	global_load_dwordx4 v[12:15], v[24:25], off offset:16
	s_nop 0
	global_load_dwordx4 v[24:27], v[24:25], off
	s_nop 0
	global_load_dwordx4 v[20:23], v[28:29], off offset:16
	s_nop 0
	global_load_dwordx4 v[28:31], v[28:29], off
	s_nop 0
	v_add_u32_e32 v158, 0x800, v158
	s_movk_i32 s3, 0x17ff
	v_add_u32_e32 v164, 64, v164
	v_add_u32_e32 v163, 64, v163
	v_add_u32_e32 v162, 64, v162
	v_add_u32_e32 v159, 64, v159
	v_add_u32_e32 v157, 0x4000, v157
	s_waitcnt vmcnt(24)
	v_pk_add_f32 v[96:97], v[166:167], v[96:97]
	s_nop 0
	v_pk_add_f32 v[96:97], v[96:97], v[100:101]
	v_pk_add_f32 v[104:105], v[170:171], v[104:105]
	v_pk_add_f32 v[96:97], v[96:97], v[108:109]
	v_pk_add_f32 v[98:99], v[168:169], v[98:99]
	v_pk_add_f32 v[104:105], v[104:105], v[112:113]
	v_pk_add_f32 v[96:97], v[96:97], v[116:117]
	v_pk_add_f32 v[98:99], v[98:99], v[102:103]
	v_pk_add_f32 v[102:103], v[104:105], v[120:121]
	v_mul_f32_e32 v105, 0x3d372713, v96
	v_mul_f32_e32 v105, v96, v105
	v_fma_f32 v105, v96, v105, v96
	v_mul_f32_e32 v105, 0x3f4c422a, v105
	v_pk_add_f32 v[106:107], v[172:173], v[106:107]
	v_add_f32_e32 v105, v105, v105
	v_pk_add_f32 v[106:107], v[106:107], v[114:115]
	v_pk_add_f32 v[102:103], v[102:103], v[124:125]
	v_mul_f32_e32 v105, 0x3fb8aa3b, v105
	v_pk_add_f32 v[100:101], v[106:107], v[122:123]
	v_mul_f32_e32 v104, 0x3d372713, v102
	v_exp_f32_e32 v106, v105
	v_mul_f32_e32 v105, 0x3d372713, v103
	v_mul_f32_e32 v104, v102, v104
	v_mul_f32_e32 v105, v103, v105
	v_fma_f32 v104, v102, v104, v102
	v_fma_f32 v105, v103, v105, v103
	v_mul_f32_e32 v104, 0x3f4c422a, v104
	v_mul_f32_e32 v105, 0x3f4c422a, v105
	v_add_f32_e32 v104, v104, v104
	v_add_f32_e32 v105, v105, v105
	v_mul_f32_e32 v104, 0x3fb8aa3b, v104
	v_mul_f32_e32 v105, 0x3fb8aa3b, v105
	v_exp_f32_e32 v104, v104
	v_exp_f32_e32 v105, v105
	v_pk_add_f32 v[98:99], v[98:99], v[110:111]
	v_pk_mul_f32 v[102:103], v[102:103], 0.5 op_sel_hi:[1,0]
	v_pk_add_f32 v[98:99], v[98:99], v[118:119]
	v_pk_add_f32 v[104:105], v[104:105], 1.0 op_sel_hi:[1,0]
	v_pk_add_f32 v[100:101], v[100:101], v[126:127]
	v_rcp_f32_e32 v108, v105
	s_nop 0
	v_add_f32_e32 v105, v108, v108
	v_rcp_f32_e32 v108, v104
	s_nop 0
	v_add_f32_e32 v104, v108, v108
	v_pk_add_f32 v[104:105], v[104:105], 1.0 op_sel_hi:[1,0] neg_lo:[1,0] neg_hi:[1,0]
	s_nop 0
	v_pk_add_f32 v[104:105], v[104:105], 1.0 op_sel_hi:[1,0]
	s_nop 0
	v_pk_mul_f32 v[102:103], v[102:103], v[104:105]
	v_mul_f32_e32 v104, 0x3d372713, v97
	v_mul_f32_e32 v104, v97, v104
	v_fma_f32 v104, v97, v104, v97
	v_mul_f32_e32 v104, 0x3f4c422a, v104
	v_add_f32_e32 v104, v104, v104
	v_mul_f32_e32 v104, 0x3fb8aa3b, v104
	v_exp_f32_e32 v107, v104
	v_pk_mul_f32 v[96:97], v[96:97], 0.5 op_sel_hi:[1,0]
	v_pk_add_f32 v[104:105], v[106:107], 1.0 op_sel_hi:[1,0]
	s_nop 0
	v_rcp_f32_e32 v107, v105
	s_nop 0
	v_add_f32_e32 v105, v107, v107
	v_rcp_f32_e32 v107, v104
	s_nop 0
	v_add_f32_e32 v104, v107, v107
	v_pk_add_f32 v[104:105], v[104:105], 1.0 op_sel_hi:[1,0] neg_lo:[1,0] neg_hi:[1,0]
	s_nop 0
	v_pk_add_f32 v[104:105], v[104:105], 1.0 op_sel_hi:[1,0]
	s_nop 0
	v_pk_mul_f32 v[104:105], v[96:97], v[104:105]
	v_mul_f32_e32 v97, 0x3d372713, v98
	v_mul_f32_e32 v97, v98, v97
	v_fma_f32 v97, v98, v97, v98
	v_mul_f32_e32 v97, 0x3f4c422a, v97
	v_add_f32_e32 v97, v97, v97
	v_mul_f32_e32 v97, 0x3fb8aa3b, v97
	v_mul_f32_e32 v96, 0x3d372713, v100
	v_exp_f32_e32 v106, v97
	v_mul_f32_e32 v97, 0x3d372713, v101
	v_mul_f32_e32 v96, v100, v96
	v_mul_f32_e32 v97, v101, v97
	v_fma_f32 v96, v100, v96, v100
	v_fma_f32 v97, v101, v97, v101
	v_mul_f32_e32 v96, 0x3f4c422a, v96
	v_mul_f32_e32 v97, 0x3f4c422a, v97
	v_add_f32_e32 v96, v96, v96
	v_add_f32_e32 v97, v97, v97
	v_mul_f32_e32 v96, 0x3fb8aa3b, v96
	v_mul_f32_e32 v97, 0x3fb8aa3b, v97
	v_exp_f32_e32 v96, v96
	v_exp_f32_e32 v97, v97
	v_pk_mul_f32 v[100:101], v[100:101], 0.5 op_sel_hi:[1,0]
	v_pk_add_f32 v[96:97], v[96:97], 1.0 op_sel_hi:[1,0]
	s_nop 0
	v_rcp_f32_e32 v108, v97
	s_nop 0
	v_add_f32_e32 v97, v108, v108
	v_rcp_f32_e32 v108, v96
	s_nop 0
	v_add_f32_e32 v96, v108, v108
	v_pk_add_f32 v[96:97], v[96:97], 1.0 op_sel_hi:[1,0] neg_lo:[1,0] neg_hi:[1,0]
	s_nop 0
	v_pk_add_f32 v[96:97], v[96:97], 1.0 op_sel_hi:[1,0]
	s_nop 0
	v_pk_mul_f32 v[100:101], v[100:101], v[96:97]
	v_mul_f32_e32 v96, 0x3d372713, v99
	v_mul_f32_e32 v96, v99, v96
	v_fma_f32 v96, v99, v96, v99
	v_mul_f32_e32 v96, 0x3f4c422a, v96
	v_add_f32_e32 v96, v96, v96
	v_mul_f32_e32 v96, 0x3fb8aa3b, v96
	v_exp_f32_e32 v107, v96
	v_pk_mul_f32 v[98:99], v[98:99], 0.5 op_sel_hi:[1,0]
	v_pk_add_f32 v[96:97], v[106:107], 1.0 op_sel_hi:[1,0]
	s_nop 0
	v_rcp_f32_e32 v107, v97
	s_nop 0
	v_add_f32_e32 v97, v107, v107
	v_rcp_f32_e32 v107, v96
	s_nop 0
	v_add_f32_e32 v96, v107, v107
	v_pk_add_f32 v[96:97], v[96:97], 1.0 op_sel_hi:[1,0] neg_lo:[1,0] neg_hi:[1,0]
	s_nop 0
	v_pk_add_f32 v[96:97], v[96:97], 1.0 op_sel_hi:[1,0]
	s_nop 0
	v_pk_mul_f32 v[106:107], v[98:99], v[96:97]
	v_cvt_pk_bf16_f32 v96, v102, v103
	v_cvt_pk_bf16_f32 v97, v100, v101
	v_cvt_pk_bf16_f32 v98, v104, v105
	v_cvt_pk_bf16_f32 v99, v106, v107
	v_lshl_add_u64 v[100:101], v[150:151], 0, v[132:133]
	global_store_dwordx4 v[100:101], v[96:99], off
	s_nop 0
	v_lshl_add_u64 v[150:151], v[150:151], 0, s[0:1]
	s_waitcnt vmcnt(17)
	v_pk_add_f32 v[64:65], v[166:167], v[64:65]
	s_nop 0
	v_pk_add_f32 v[64:65], v[64:65], v[68:69]
	v_pk_add_f32 v[72:73], v[170:171], v[72:73]
	v_pk_add_f32 v[64:65], v[64:65], v[76:77]
	v_pk_add_f32 v[66:67], v[168:169], v[66:67]
	v_pk_add_f32 v[72:73], v[72:73], v[80:81]
	v_pk_add_f32 v[64:65], v[64:65], v[84:85]
	v_pk_add_f32 v[66:67], v[66:67], v[70:71]
	v_pk_add_f32 v[70:71], v[72:73], v[88:89]
	v_mul_f32_e32 v73, 0x3d372713, v64
	v_mul_f32_e32 v73, v64, v73
	v_fma_f32 v73, v64, v73, v64
	v_mul_f32_e32 v73, 0x3f4c422a, v73
	v_pk_add_f32 v[74:75], v[172:173], v[74:75]
	v_add_f32_e32 v73, v73, v73
	v_pk_add_f32 v[74:75], v[74:75], v[82:83]
	v_pk_add_f32 v[70:71], v[70:71], v[92:93]
	v_mul_f32_e32 v73, 0x3fb8aa3b, v73
	v_pk_add_f32 v[68:69], v[74:75], v[90:91]
	v_mul_f32_e32 v72, 0x3d372713, v70
	v_exp_f32_e32 v74, v73
	v_mul_f32_e32 v73, 0x3d372713, v71
	v_mul_f32_e32 v72, v70, v72
	v_mul_f32_e32 v73, v71, v73
	v_fma_f32 v72, v70, v72, v70
	v_fma_f32 v73, v71, v73, v71
	v_mul_f32_e32 v72, 0x3f4c422a, v72
	v_mul_f32_e32 v73, 0x3f4c422a, v73
	v_add_f32_e32 v72, v72, v72
	v_add_f32_e32 v73, v73, v73
	v_mul_f32_e32 v72, 0x3fb8aa3b, v72
	v_mul_f32_e32 v73, 0x3fb8aa3b, v73
	v_exp_f32_e32 v72, v72
	v_exp_f32_e32 v73, v73
	v_pk_add_f32 v[66:67], v[66:67], v[78:79]
	v_pk_mul_f32 v[70:71], v[70:71], 0.5 op_sel_hi:[1,0]
	v_pk_add_f32 v[66:67], v[66:67], v[86:87]
	v_pk_add_f32 v[72:73], v[72:73], 1.0 op_sel_hi:[1,0]
	v_pk_add_f32 v[68:69], v[68:69], v[94:95]
	v_rcp_f32_e32 v76, v73
	s_nop 0
	v_add_f32_e32 v73, v76, v76
	v_rcp_f32_e32 v76, v72
	s_nop 0
	v_add_f32_e32 v72, v76, v76
	v_pk_add_f32 v[72:73], v[72:73], 1.0 op_sel_hi:[1,0] neg_lo:[1,0] neg_hi:[1,0]
	s_nop 0
	v_pk_add_f32 v[72:73], v[72:73], 1.0 op_sel_hi:[1,0]
	s_nop 0
	v_pk_mul_f32 v[70:71], v[70:71], v[72:73]
	v_mul_f32_e32 v72, 0x3d372713, v65
	v_mul_f32_e32 v72, v65, v72
	v_fma_f32 v72, v65, v72, v65
	v_mul_f32_e32 v72, 0x3f4c422a, v72
	v_add_f32_e32 v72, v72, v72
	v_mul_f32_e32 v72, 0x3fb8aa3b, v72
	v_exp_f32_e32 v75, v72
	v_pk_mul_f32 v[64:65], v[64:65], 0.5 op_sel_hi:[1,0]
	v_pk_add_f32 v[72:73], v[74:75], 1.0 op_sel_hi:[1,0]
	s_nop 0
	v_rcp_f32_e32 v75, v73
	s_nop 0
	v_add_f32_e32 v73, v75, v75
	v_rcp_f32_e32 v75, v72
	s_nop 0
	v_add_f32_e32 v72, v75, v75
	v_pk_add_f32 v[72:73], v[72:73], 1.0 op_sel_hi:[1,0] neg_lo:[1,0] neg_hi:[1,0]
	s_nop 0
	v_pk_add_f32 v[72:73], v[72:73], 1.0 op_sel_hi:[1,0]
	s_nop 0
	v_pk_mul_f32 v[72:73], v[64:65], v[72:73]
	v_mul_f32_e32 v65, 0x3d372713, v66
	v_mul_f32_e32 v65, v66, v65
	v_fma_f32 v65, v66, v65, v66
	v_mul_f32_e32 v65, 0x3f4c422a, v65
	v_add_f32_e32 v65, v65, v65
	v_mul_f32_e32 v65, 0x3fb8aa3b, v65
	v_mul_f32_e32 v64, 0x3d372713, v68
	v_exp_f32_e32 v74, v65
	v_mul_f32_e32 v65, 0x3d372713, v69
	v_mul_f32_e32 v64, v68, v64
	v_mul_f32_e32 v65, v69, v65
	v_fma_f32 v64, v68, v64, v68
	v_fma_f32 v65, v69, v65, v69
	v_mul_f32_e32 v64, 0x3f4c422a, v64
	v_mul_f32_e32 v65, 0x3f4c422a, v65
	v_add_f32_e32 v64, v64, v64
	v_add_f32_e32 v65, v65, v65
	v_mul_f32_e32 v64, 0x3fb8aa3b, v64
	v_mul_f32_e32 v65, 0x3fb8aa3b, v65
	v_exp_f32_e32 v64, v64
	v_exp_f32_e32 v65, v65
	v_pk_mul_f32 v[68:69], v[68:69], 0.5 op_sel_hi:[1,0]
	v_pk_add_f32 v[64:65], v[64:65], 1.0 op_sel_hi:[1,0]
	s_nop 0
	v_rcp_f32_e32 v76, v65
	s_nop 0
	v_add_f32_e32 v65, v76, v76
	v_rcp_f32_e32 v76, v64
	s_nop 0
	v_add_f32_e32 v64, v76, v76
	v_pk_add_f32 v[64:65], v[64:65], 1.0 op_sel_hi:[1,0] neg_lo:[1,0] neg_hi:[1,0]
	s_nop 0
	v_pk_add_f32 v[64:65], v[64:65], 1.0 op_sel_hi:[1,0]
	s_nop 0
	v_pk_mul_f32 v[68:69], v[68:69], v[64:65]
	v_mul_f32_e32 v64, 0x3d372713, v67
	v_mul_f32_e32 v64, v67, v64
	v_fma_f32 v64, v67, v64, v67
	v_mul_f32_e32 v64, 0x3f4c422a, v64
	v_add_f32_e32 v64, v64, v64
	v_mul_f32_e32 v64, 0x3fb8aa3b, v64
	v_exp_f32_e32 v75, v64
	v_pk_mul_f32 v[66:67], v[66:67], 0.5 op_sel_hi:[1,0]
	v_pk_add_f32 v[64:65], v[74:75], 1.0 op_sel_hi:[1,0]
	s_nop 0
	v_rcp_f32_e32 v75, v65
	s_nop 0
	v_add_f32_e32 v65, v75, v75
	v_rcp_f32_e32 v75, v64
	s_nop 0
	v_add_f32_e32 v64, v75, v75
	v_pk_add_f32 v[64:65], v[64:65], 1.0 op_sel_hi:[1,0] neg_lo:[1,0] neg_hi:[1,0]
	s_nop 0
	v_pk_add_f32 v[64:65], v[64:65], 1.0 op_sel_hi:[1,0]
	s_nop 0
	v_pk_mul_f32 v[74:75], v[66:67], v[64:65]
	v_cvt_pk_bf16_f32 v64, v70, v71
	v_cvt_pk_bf16_f32 v65, v68, v69
	v_cvt_pk_bf16_f32 v66, v72, v73
	v_cvt_pk_bf16_f32 v67, v74, v75
	v_lshl_add_u64 v[68:69], v[144:145], 0, v[132:133]
	global_store_dwordx4 v[68:69], v[64:67], off
	s_nop 0
	v_lshl_add_u64 v[144:145], v[144:145], 0, s[0:1]
	s_waitcnt vmcnt(10)
	v_pk_add_f32 v[32:33], v[166:167], v[32:33]
	s_nop 0
	v_pk_add_f32 v[32:33], v[32:33], v[36:37]
	v_pk_add_f32 v[40:41], v[170:171], v[40:41]
	v_pk_add_f32 v[32:33], v[32:33], v[44:45]
	v_pk_add_f32 v[34:35], v[168:169], v[34:35]
	v_pk_add_f32 v[40:41], v[40:41], v[48:49]
	v_pk_add_f32 v[32:33], v[32:33], v[52:53]
	v_pk_add_f32 v[34:35], v[34:35], v[38:39]
	v_pk_add_f32 v[38:39], v[40:41], v[56:57]
	v_mul_f32_e32 v41, 0x3d372713, v32
	v_mul_f32_e32 v41, v32, v41
	v_fma_f32 v41, v32, v41, v32
	v_mul_f32_e32 v41, 0x3f4c422a, v41
	v_pk_add_f32 v[42:43], v[172:173], v[42:43]
	v_add_f32_e32 v41, v41, v41
	v_pk_add_f32 v[42:43], v[42:43], v[50:51]
	v_pk_add_f32 v[38:39], v[38:39], v[60:61]
	v_mul_f32_e32 v41, 0x3fb8aa3b, v41
	v_pk_add_f32 v[36:37], v[42:43], v[58:59]
	v_mul_f32_e32 v40, 0x3d372713, v38
	v_exp_f32_e32 v42, v41
	v_mul_f32_e32 v41, 0x3d372713, v39
	v_mul_f32_e32 v40, v38, v40
	v_mul_f32_e32 v41, v39, v41
	v_fma_f32 v40, v38, v40, v38
	v_fma_f32 v41, v39, v41, v39
	v_mul_f32_e32 v40, 0x3f4c422a, v40
	v_mul_f32_e32 v41, 0x3f4c422a, v41
	v_add_f32_e32 v40, v40, v40
	v_add_f32_e32 v41, v41, v41
	v_mul_f32_e32 v40, 0x3fb8aa3b, v40
	v_mul_f32_e32 v41, 0x3fb8aa3b, v41
	v_exp_f32_e32 v40, v40
	v_exp_f32_e32 v41, v41
	v_pk_add_f32 v[34:35], v[34:35], v[46:47]
	v_pk_mul_f32 v[38:39], v[38:39], 0.5 op_sel_hi:[1,0]
	v_pk_add_f32 v[34:35], v[34:35], v[54:55]
	v_pk_add_f32 v[40:41], v[40:41], 1.0 op_sel_hi:[1,0]
	v_pk_add_f32 v[36:37], v[36:37], v[62:63]
	v_rcp_f32_e32 v44, v41
	s_nop 0
	v_add_f32_e32 v41, v44, v44
	v_rcp_f32_e32 v44, v40
	s_nop 0
	v_add_f32_e32 v40, v44, v44
	v_pk_add_f32 v[40:41], v[40:41], 1.0 op_sel_hi:[1,0] neg_lo:[1,0] neg_hi:[1,0]
	s_nop 0
	v_pk_add_f32 v[40:41], v[40:41], 1.0 op_sel_hi:[1,0]
	s_nop 0
	v_pk_mul_f32 v[38:39], v[38:39], v[40:41]
	v_mul_f32_e32 v40, 0x3d372713, v33
	v_mul_f32_e32 v40, v33, v40
	v_fma_f32 v40, v33, v40, v33
	v_mul_f32_e32 v40, 0x3f4c422a, v40
	v_add_f32_e32 v40, v40, v40
	v_mul_f32_e32 v40, 0x3fb8aa3b, v40
	v_exp_f32_e32 v43, v40
	v_pk_mul_f32 v[32:33], v[32:33], 0.5 op_sel_hi:[1,0]
	v_pk_add_f32 v[40:41], v[42:43], 1.0 op_sel_hi:[1,0]
	s_nop 0
	v_rcp_f32_e32 v43, v41
	s_nop 0
	v_add_f32_e32 v41, v43, v43
	v_rcp_f32_e32 v43, v40
	s_nop 0
	v_add_f32_e32 v40, v43, v43
	v_pk_add_f32 v[40:41], v[40:41], 1.0 op_sel_hi:[1,0] neg_lo:[1,0] neg_hi:[1,0]
	s_nop 0
	v_pk_add_f32 v[40:41], v[40:41], 1.0 op_sel_hi:[1,0]
	s_nop 0
	v_pk_mul_f32 v[40:41], v[32:33], v[40:41]
	v_mul_f32_e32 v33, 0x3d372713, v34
	v_mul_f32_e32 v33, v34, v33
	v_fma_f32 v33, v34, v33, v34
	v_mul_f32_e32 v33, 0x3f4c422a, v33
	v_add_f32_e32 v33, v33, v33
	v_mul_f32_e32 v33, 0x3fb8aa3b, v33
	v_mul_f32_e32 v32, 0x3d372713, v36
	v_exp_f32_e32 v42, v33
	v_mul_f32_e32 v33, 0x3d372713, v37
	v_mul_f32_e32 v32, v36, v32
	v_mul_f32_e32 v33, v37, v33
	v_fma_f32 v32, v36, v32, v36
	v_fma_f32 v33, v37, v33, v37
	v_mul_f32_e32 v32, 0x3f4c422a, v32
	v_mul_f32_e32 v33, 0x3f4c422a, v33
	v_add_f32_e32 v32, v32, v32
	v_add_f32_e32 v33, v33, v33
	v_mul_f32_e32 v32, 0x3fb8aa3b, v32
	v_mul_f32_e32 v33, 0x3fb8aa3b, v33
	v_exp_f32_e32 v32, v32
	v_exp_f32_e32 v33, v33
	v_pk_mul_f32 v[36:37], v[36:37], 0.5 op_sel_hi:[1,0]
	v_pk_add_f32 v[32:33], v[32:33], 1.0 op_sel_hi:[1,0]
	s_nop 0
	v_rcp_f32_e32 v44, v33
	s_nop 0
	v_add_f32_e32 v33, v44, v44
	v_rcp_f32_e32 v44, v32
	s_nop 0
	v_add_f32_e32 v32, v44, v44
	v_pk_add_f32 v[32:33], v[32:33], 1.0 op_sel_hi:[1,0] neg_lo:[1,0] neg_hi:[1,0]
	s_nop 0
	v_pk_add_f32 v[32:33], v[32:33], 1.0 op_sel_hi:[1,0]
	s_nop 0
	v_pk_mul_f32 v[36:37], v[36:37], v[32:33]
	v_mul_f32_e32 v32, 0x3d372713, v35
	v_mul_f32_e32 v32, v35, v32
	v_fma_f32 v32, v35, v32, v35
	v_mul_f32_e32 v32, 0x3f4c422a, v32
	v_add_f32_e32 v32, v32, v32
	v_mul_f32_e32 v32, 0x3fb8aa3b, v32
	v_exp_f32_e32 v43, v32
	v_pk_mul_f32 v[34:35], v[34:35], 0.5 op_sel_hi:[1,0]
	v_pk_add_f32 v[32:33], v[42:43], 1.0 op_sel_hi:[1,0]
	s_nop 0
	v_rcp_f32_e32 v43, v33
	s_nop 0
	v_add_f32_e32 v33, v43, v43
	v_rcp_f32_e32 v43, v32
	s_nop 0
	v_add_f32_e32 v32, v43, v43
	v_pk_add_f32 v[32:33], v[32:33], 1.0 op_sel_hi:[1,0] neg_lo:[1,0] neg_hi:[1,0]
	s_nop 0
	v_pk_add_f32 v[32:33], v[32:33], 1.0 op_sel_hi:[1,0]
	s_nop 0
	v_pk_mul_f32 v[42:43], v[34:35], v[32:33]
	v_cvt_pk_bf16_f32 v32, v38, v39
	v_cvt_pk_bf16_f32 v33, v36, v37
	v_cvt_pk_bf16_f32 v34, v40, v41
	v_cvt_pk_bf16_f32 v35, v42, v43
	v_lshl_add_u64 v[36:37], v[146:147], 0, v[132:133]
	global_store_dwordx4 v[36:37], v[32:35], off
	s_nop 0
	v_lshl_add_u64 v[146:147], v[146:147], 0, s[0:1]
	s_waitcnt vmcnt(3)
	v_pk_add_f32 v[0:1], v[166:167], v[0:1]
	s_nop 0
	v_pk_add_f32 v[0:1], v[0:1], v[4:5]
	v_pk_add_f32 v[8:9], v[170:171], v[8:9]
	v_pk_add_f32 v[0:1], v[0:1], v[12:13]
	v_pk_add_f32 v[2:3], v[168:169], v[2:3]
	v_pk_add_f32 v[8:9], v[8:9], v[16:17]
	v_pk_add_f32 v[0:1], v[0:1], v[20:21]
	v_pk_add_f32 v[2:3], v[2:3], v[6:7]
	v_pk_add_f32 v[6:7], v[8:9], v[24:25]
	v_mul_f32_e32 v9, 0x3d372713, v0
	v_mul_f32_e32 v9, v0, v9
	v_fma_f32 v9, v0, v9, v0
	v_mul_f32_e32 v9, 0x3f4c422a, v9
	v_pk_add_f32 v[10:11], v[172:173], v[10:11]
	v_add_f32_e32 v9, v9, v9
	v_pk_add_f32 v[10:11], v[10:11], v[18:19]
	v_pk_add_f32 v[6:7], v[6:7], v[28:29]
	v_mul_f32_e32 v9, 0x3fb8aa3b, v9
	v_pk_add_f32 v[4:5], v[10:11], v[26:27]
	v_mul_f32_e32 v8, 0x3d372713, v6
	v_exp_f32_e32 v10, v9
	v_mul_f32_e32 v9, 0x3d372713, v7
	v_mul_f32_e32 v8, v6, v8
	v_mul_f32_e32 v9, v7, v9
	v_fma_f32 v8, v6, v8, v6
	v_fma_f32 v9, v7, v9, v7
	v_mul_f32_e32 v8, 0x3f4c422a, v8
	v_mul_f32_e32 v9, 0x3f4c422a, v9
	v_add_f32_e32 v8, v8, v8
	v_add_f32_e32 v9, v9, v9
	v_mul_f32_e32 v8, 0x3fb8aa3b, v8
	v_mul_f32_e32 v9, 0x3fb8aa3b, v9
	v_exp_f32_e32 v8, v8
	v_exp_f32_e32 v9, v9
	v_pk_add_f32 v[2:3], v[2:3], v[14:15]
	v_pk_mul_f32 v[6:7], v[6:7], 0.5 op_sel_hi:[1,0]
	v_pk_add_f32 v[2:3], v[2:3], v[22:23]
	v_pk_add_f32 v[8:9], v[8:9], 1.0 op_sel_hi:[1,0]
	v_pk_add_f32 v[4:5], v[4:5], v[30:31]
	v_rcp_f32_e32 v12, v9
	s_nop 0
	v_add_f32_e32 v9, v12, v12
	v_rcp_f32_e32 v12, v8
	s_nop 0
	v_add_f32_e32 v8, v12, v12
	v_pk_add_f32 v[8:9], v[8:9], 1.0 op_sel_hi:[1,0] neg_lo:[1,0] neg_hi:[1,0]
	s_nop 0
	v_pk_add_f32 v[8:9], v[8:9], 1.0 op_sel_hi:[1,0]
	s_nop 0
	v_pk_mul_f32 v[6:7], v[6:7], v[8:9]
	v_mul_f32_e32 v8, 0x3d372713, v1
	v_mul_f32_e32 v8, v1, v8
	v_fma_f32 v8, v1, v8, v1
	v_mul_f32_e32 v8, 0x3f4c422a, v8
	v_add_f32_e32 v8, v8, v8
	v_mul_f32_e32 v8, 0x3fb8aa3b, v8
	v_exp_f32_e32 v11, v8
	v_pk_mul_f32 v[0:1], v[0:1], 0.5 op_sel_hi:[1,0]
	v_pk_add_f32 v[8:9], v[10:11], 1.0 op_sel_hi:[1,0]
	s_nop 0
	v_rcp_f32_e32 v11, v9
	s_nop 0
	v_add_f32_e32 v9, v11, v11
	v_rcp_f32_e32 v11, v8
	s_nop 0
	v_add_f32_e32 v8, v11, v11
	v_pk_add_f32 v[8:9], v[8:9], 1.0 op_sel_hi:[1,0] neg_lo:[1,0] neg_hi:[1,0]
	s_nop 0
	v_pk_add_f32 v[8:9], v[8:9], 1.0 op_sel_hi:[1,0]
	s_nop 0
	v_pk_mul_f32 v[8:9], v[0:1], v[8:9]
	v_mul_f32_e32 v1, 0x3d372713, v2
	v_mul_f32_e32 v1, v2, v1
	v_fma_f32 v1, v2, v1, v2
	v_mul_f32_e32 v1, 0x3f4c422a, v1
	v_add_f32_e32 v1, v1, v1
	v_mul_f32_e32 v1, 0x3fb8aa3b, v1
	v_mul_f32_e32 v0, 0x3d372713, v4
	v_exp_f32_e32 v10, v1
	v_mul_f32_e32 v1, 0x3d372713, v5
	v_mul_f32_e32 v0, v4, v0
	v_mul_f32_e32 v1, v5, v1
	v_fma_f32 v0, v4, v0, v4
	v_fma_f32 v1, v5, v1, v5
	v_mul_f32_e32 v0, 0x3f4c422a, v0
	v_mul_f32_e32 v1, 0x3f4c422a, v1
	v_add_f32_e32 v0, v0, v0
	v_add_f32_e32 v1, v1, v1
	v_mul_f32_e32 v0, 0x3fb8aa3b, v0
	v_mul_f32_e32 v1, 0x3fb8aa3b, v1
	v_exp_f32_e32 v0, v0
	v_exp_f32_e32 v1, v1
	v_pk_mul_f32 v[4:5], v[4:5], 0.5 op_sel_hi:[1,0]
	v_pk_add_f32 v[0:1], v[0:1], 1.0 op_sel_hi:[1,0]
	s_nop 0
	v_rcp_f32_e32 v12, v1
	s_nop 0
	v_add_f32_e32 v1, v12, v12
	v_rcp_f32_e32 v12, v0
	s_nop 0
	v_add_f32_e32 v0, v12, v12
	v_pk_add_f32 v[0:1], v[0:1], 1.0 op_sel_hi:[1,0] neg_lo:[1,0] neg_hi:[1,0]
	s_nop 0
	v_pk_add_f32 v[0:1], v[0:1], 1.0 op_sel_hi:[1,0]
	s_nop 0
	v_pk_mul_f32 v[4:5], v[4:5], v[0:1]
	v_mul_f32_e32 v0, 0x3d372713, v3
	v_mul_f32_e32 v0, v3, v0
	v_fma_f32 v0, v3, v0, v3
	v_mul_f32_e32 v0, 0x3f4c422a, v0
	v_add_f32_e32 v0, v0, v0
	v_mul_f32_e32 v0, 0x3fb8aa3b, v0
	v_exp_f32_e32 v11, v0
	v_pk_mul_f32 v[2:3], v[2:3], 0.5 op_sel_hi:[1,0]
	v_pk_add_f32 v[0:1], v[10:11], 1.0 op_sel_hi:[1,0]
	s_nop 0
	v_rcp_f32_e32 v11, v1
	s_nop 0
	v_add_f32_e32 v1, v11, v11
	v_rcp_f32_e32 v11, v0
	s_nop 0
	v_add_f32_e32 v0, v11, v11
	v_pk_add_f32 v[0:1], v[0:1], 1.0 op_sel_hi:[1,0] neg_lo:[1,0] neg_hi:[1,0]
	v_cmp_lt_u32_e32 vcc, s3, v158
	v_pk_add_f32 v[0:1], v[0:1], 1.0 op_sel_hi:[1,0]
	s_or_b64 s[4:5], vcc, s[4:5]
	v_pk_mul_f32 v[10:11], v[2:3], v[0:1]
	v_cvt_pk_bf16_f32 v0, v6, v7
	v_cvt_pk_bf16_f32 v1, v4, v5
	v_cvt_pk_bf16_f32 v2, v8, v9
	v_cvt_pk_bf16_f32 v3, v10, v11
	v_lshl_add_u64 v[4:5], v[148:149], 0, v[132:133]
	v_lshl_add_u64 v[148:149], v[148:149], 0, s[0:1]
	global_store_dwordx4 v[4:5], v[0:3], off
	s_andn2_b64 exec, exec, s[4:5]
	s_cbranch_execnz .LBB0_712
	s_or_b64 exec, exec, s[4:5]
	s_add_i32 s8, s8, 1
	s_mov_b64 s[4:5], 0
	s_branch .LBB0_703
